# plus: first K-step of a prefetched tile waits vmcnt(32) (prefetch DMAs only) instead of draining the 32 epilogue stores, in FF1 / out-proj / FF2
# speedup vs baseline: 1.0118x; 1.0027x over previous
; template <int MI, bool SWAP, class Epi> ...
;     ...
;         if (kt + 1 < nk && !(prefetched && kt == 0)) { if (MI == 8) asm volatile("s_waitcnt vmcnt(6)\n\ts_barrier" ::: "memory"); else if (MI == 4) asm volatile("s_waitcnt vmcnt(4)\n\ts_barrier" ::: "memory"); else asm volatile("s_waitcnt vmcnt(3)\n\ts_barrier" ::: "memory"); }
;         else asm volatile("s_waitcnt vmcnt(0)\n\ts_barrier" ::: "memory");
.LBB0_1968:
	s_andn2_b64 vcc, exec, s[0:1]
	s_cbranch_vccnz .LBB0_1970
	s_waitcnt vmcnt(32)
	s_barrier
